# attention band-edge mask blocks: alternating mask registers, hazard nops removed (64 -> 49 slots per block)
# baseline (speedup 1.0000x reference)
.LBB0_320:
	ds_read_b128 v[168:171], v213
	ds_read_b128 v[164:167], v213 offset:32
	ds_read_b128 v[10:13], v213 offset:64
	ds_read_b128 v[160:163], v213 offset:96
	v_cndmask_b32_e64 v0, 0, 1, s[34:35]
	s_add_i32 s33, s3, 0xffffff7f
	s_waitcnt lgkmcnt(3)
	v_mfma_f32_32x32x16_bf16 v[80:95], v[168:171], v[96:99], 0
	v_cmp_ne_u32_e64 s[38:39], 1, v0
	s_andn2_b64 vcc, exec, s[34:35]
	s_waitcnt lgkmcnt(2)
	v_mfma_f32_32x32x16_bf16 v[80:95], v[164:167], v[100:103], v[80:95]
	s_waitcnt lgkmcnt(1)
	v_mfma_f32_32x32x16_bf16 v[80:95], v[10:13], v[104:107], v[80:95]
	s_waitcnt lgkmcnt(0)
	v_mfma_f32_32x32x16_bf16 v[80:95], v[160:163], v[108:111], v[80:95]
	s_cbranch_vccnz .LBB0_323
	s_cmp_lt_i32 s3, s46
	s_cselect_b64 s[0:1], -1, 0
	s_cmp_gt_i32 s3, s75
	s_cselect_b64 s[26:27], -1, 0
	s_or_b64 s[0:1], s[0:1], s[26:27]
	s_andn2_b64 vcc, exec, s[0:1]
	s_cbranch_vccnz .LBB0_323
	s_sub_i32 s0, s33, s54
	v_add_u32_e32 v0, s0, v214
	v_cmp_lt_u32_e32 vcc, s66, v0
	v_add_u32_e32 v255, s0, v215
	v_cmp_lt_u32_e64 s[26:27], s66, v255
	v_cndmask_b32_e32 v80, v200, v80, vcc
	v_add_u32_e32 v0, s0, v216
	v_cmp_lt_u32_e32 vcc, s66, v0
	v_cndmask_b32_e64 v81, v200, v81, s[26:27]
	v_add_u32_e32 v255, s0, v217
	v_cmp_lt_u32_e64 s[26:27], s66, v255
	v_cndmask_b32_e32 v82, v200, v82, vcc
	v_add_u32_e32 v0, s0, v218
	v_cmp_lt_u32_e32 vcc, s66, v0
	v_cndmask_b32_e64 v83, v200, v83, s[26:27]
	v_add_u32_e32 v255, s0, v219
	v_cmp_lt_u32_e64 s[26:27], s66, v255
	v_cndmask_b32_e32 v84, v200, v84, vcc
	v_add_u32_e32 v0, s0, v220
	v_cmp_lt_u32_e32 vcc, s66, v0
	v_cndmask_b32_e64 v85, v200, v85, s[26:27]
	v_add_u32_e32 v255, s0, v221
	v_cmp_lt_u32_e64 s[26:27], s66, v255
	v_cndmask_b32_e32 v86, v200, v86, vcc
	v_add_u32_e32 v0, s0, v222
	v_cmp_lt_u32_e32 vcc, s66, v0
	v_cndmask_b32_e64 v87, v200, v87, s[26:27]
	v_add_u32_e32 v255, s0, v223
	v_cmp_lt_u32_e64 s[26:27], s66, v255
	v_cndmask_b32_e32 v88, v200, v88, vcc
	v_add_u32_e32 v0, s0, v224
	v_cmp_lt_u32_e32 vcc, s66, v0
	v_cndmask_b32_e64 v89, v200, v89, s[26:27]
	v_add_u32_e32 v255, s0, v225
	v_cmp_lt_u32_e64 s[26:27], s66, v255
	v_cndmask_b32_e32 v90, v200, v90, vcc
	v_add_u32_e32 v0, s0, v226
	v_cmp_lt_u32_e32 vcc, s66, v0
	v_cndmask_b32_e64 v91, v200, v91, s[26:27]
	v_add_u32_e32 v255, s0, v227
	v_cmp_lt_u32_e64 s[26:27], s66, v255
	v_cndmask_b32_e32 v92, v200, v92, vcc
	v_add_u32_e32 v0, s0, v228
	v_cmp_lt_u32_e32 vcc, s66, v0
	v_cndmask_b32_e64 v93, v200, v93, s[26:27]
	v_add_u32_e32 v255, s0, v229
	v_cmp_lt_u32_e64 s[26:27], s66, v255
	v_cndmask_b32_e32 v94, v200, v94, vcc
	s_nop 0
	v_cndmask_b32_e64 v95, v200, v95, s[26:27]
.LBB0_323:
	s_nop 10
	v_max3_f32 v0, v80, s18, v81
	v_max3_f32 v0, v0, v82, v83
	v_max3_f32 v0, v0, v84, v85
	v_max3_f32 v0, v0, v86, v87
	v_max3_f32 v0, v0, v88, v89
	v_max3_f32 v0, v0, v90, v91
	v_max3_f32 v0, v0, v92, v93
	v_max3_f32 v0, v0, v94, v95
	v_mov_b32_e32 v2, v0
	v_mov_b32_e32 v255, v0
	s_nop 1
	v_permlane32_swap_b32_e32 v2, v255
	s_and_b64 vcc, exec, s[38:39]
	s_waitcnt lgkmcnt(0)
	v_max3_f32 v234, v231, v2, v255
	v_sub_f32_e32 v255, v234, v231
	v_cmp_lt_f32_e64 s[98:99], 4.0, v255
	s_nop 1
	v_cndmask_b32_e64 v234, v231, v234, s[98:99]
	v_sub_f32_e32 v2, v81, v234
	v_exp_f32_e32 v14, v2
	v_sub_f32_e32 v2, v82, v234
	v_exp_f32_e32 v232, v2
	v_sub_f32_e32 v2, v83, v234
	v_exp_f32_e32 v236, v2
	v_sub_f32_e32 v2, v84, v234
	v_exp_f32_e32 v237, v2
	v_sub_f32_e32 v2, v85, v234
	v_exp_f32_e32 v238, v2
	v_sub_f32_e32 v2, v86, v234
	v_exp_f32_e32 v239, v2
	v_sub_f32_e32 v2, v87, v234
	v_exp_f32_e32 v240, v2
	v_sub_f32_e32 v2, v88, v234
	v_exp_f32_e32 v241, v2
	v_sub_f32_e32 v2, v89, v234
	v_exp_f32_e32 v242, v2
	v_sub_f32_e32 v2, v90, v234
	v_exp_f32_e32 v243, v2
	v_sub_f32_e32 v2, v91, v234
	v_exp_f32_e32 v244, v2
	v_sub_f32_e32 v2, v92, v234
	v_exp_f32_e32 v245, v2
	v_sub_f32_e32 v2, v93, v234
	v_exp_f32_e32 v246, v2
	v_sub_f32_e32 v2, v94, v234
	v_sub_f32_e32 v0, v80, v234
	v_exp_f32_e32 v247, v2
	v_sub_f32_e32 v2, v95, v234
	v_mfma_f32_32x32x16_bf16 v[80:95], v[168:171], v[112:115], 0
	v_exp_f32_e32 v0, v0
	v_exp_f32_e32 v248, v2
	v_cvt_pk_bf16_f32 v6, v0, v14
	v_cvt_pk_bf16_f32 v7, v232, v236
	v_cvt_pk_bf16_f32 v8, v237, v238
	v_cvt_pk_bf16_f32 v9, v239, v240
	v_cvt_pk_bf16_f32 v2, v241, v242
	v_mfma_f32_32x32x16_bf16 v[80:95], v[164:167], v[116:119], v[80:95]
	v_cvt_pk_bf16_f32 v3, v243, v244
	v_cvt_pk_bf16_f32 v4, v245, v246
	v_cvt_pk_bf16_f32 v5, v247, v248
	v_mfma_f32_32x32x16_bf16 v[80:95], v[10:13], v[120:123], v[80:95]
	v_mfma_f32_32x32x16_bf16 v[80:95], v[160:163], v[124:127], v[80:95]
	s_cbranch_vccnz .LBB0_326
	s_cmp_lt_i32 s3, s62
	s_cselect_b64 s[0:1], -1, 0
	s_cmp_gt_i32 s3, s55
	s_cselect_b64 s[26:27], -1, 0
	s_or_b64 s[0:1], s[0:1], s[26:27]
	s_andn2_b64 vcc, exec, s[0:1]
	s_cbranch_vccnz .LBB0_326
	s_sub_i32 s0, s33, s63
	v_add_u32_e32 v10, s0, v214
	v_cmp_lt_u32_e32 vcc, s66, v10
	v_add_u32_e32 v255, s0, v215
	v_cmp_lt_u32_e64 s[26:27], s66, v255
	v_cndmask_b32_e32 v80, v200, v80, vcc
	v_add_u32_e32 v10, s0, v216
	v_cmp_lt_u32_e32 vcc, s66, v10
	v_cndmask_b32_e64 v81, v200, v81, s[26:27]
	v_add_u32_e32 v255, s0, v217
	v_cmp_lt_u32_e64 s[26:27], s66, v255
	v_cndmask_b32_e32 v82, v200, v82, vcc
	v_add_u32_e32 v10, s0, v218
	v_cmp_lt_u32_e32 vcc, s66, v10
	v_cndmask_b32_e64 v83, v200, v83, s[26:27]
	v_add_u32_e32 v255, s0, v219
	v_cmp_lt_u32_e64 s[26:27], s66, v255
	v_cndmask_b32_e32 v84, v200, v84, vcc
	v_add_u32_e32 v10, s0, v220
	v_cmp_lt_u32_e32 vcc, s66, v10
	v_cndmask_b32_e64 v85, v200, v85, s[26:27]
	v_add_u32_e32 v255, s0, v221
	v_cmp_lt_u32_e64 s[26:27], s66, v255
	v_cndmask_b32_e32 v86, v200, v86, vcc
	v_add_u32_e32 v10, s0, v222
	v_cmp_lt_u32_e32 vcc, s66, v10
	v_cndmask_b32_e64 v87, v200, v87, s[26:27]
	v_add_u32_e32 v255, s0, v223
	v_cmp_lt_u32_e64 s[26:27], s66, v255
	v_cndmask_b32_e32 v88, v200, v88, vcc
	v_add_u32_e32 v10, s0, v224
	v_cmp_lt_u32_e32 vcc, s66, v10
	v_cndmask_b32_e64 v89, v200, v89, s[26:27]
	v_add_u32_e32 v255, s0, v225
	v_cmp_lt_u32_e64 s[26:27], s66, v255
	v_cndmask_b32_e32 v90, v200, v90, vcc
	v_add_u32_e32 v10, s0, v226
	v_cmp_lt_u32_e32 vcc, s66, v10
	v_cndmask_b32_e64 v91, v200, v91, s[26:27]
	v_add_u32_e32 v255, s0, v227
	v_cmp_lt_u32_e64 s[26:27], s66, v255
	v_cndmask_b32_e32 v92, v200, v92, vcc
	v_add_u32_e32 v10, s0, v228
	v_cmp_lt_u32_e32 vcc, s66, v10
	v_cndmask_b32_e64 v93, v200, v93, s[26:27]
	v_add_u32_e32 v255, s0, v229
	v_cmp_lt_u32_e64 s[26:27], s66, v255
	v_cndmask_b32_e32 v94, v200, v94, vcc
	s_nop 0
	v_cndmask_b32_e64 v95, v200, v95, s[26:27]

.LBB0_341:
	ds_read_b128 v[168:171], v213 offset:9728
	ds_read_b128 v[164:167], v213 offset:9760
	ds_read_b128 v[10:13], v213 offset:9792
	ds_read_b128 v[160:163], v213 offset:9824
	v_cndmask_b32_e64 v2, 0, 1, s[34:35]
	s_add_i32 s33, s3, 0xffffff7f
	s_waitcnt lgkmcnt(3)
	v_mfma_f32_32x32x16_bf16 v[80:95], v[168:171], v[96:99], 0
	v_cmp_ne_u32_e64 s[40:41], 1, v2
	s_andn2_b64 vcc, exec, s[34:35]
	s_waitcnt lgkmcnt(2)
	v_mfma_f32_32x32x16_bf16 v[80:95], v[164:167], v[100:103], v[80:95]
	s_waitcnt lgkmcnt(1)
	v_mfma_f32_32x32x16_bf16 v[80:95], v[10:13], v[104:107], v[80:95]
	s_waitcnt lgkmcnt(0)
	v_mfma_f32_32x32x16_bf16 v[80:95], v[160:163], v[108:111], v[80:95]
	s_cbranch_vccnz .LBB0_344
	s_cmp_lt_i32 s3, s46
	s_cselect_b64 s[0:1], -1, 0
	s_cmp_gt_i32 s3, s75
	s_cselect_b64 s[26:27], -1, 0
	s_or_b64 s[0:1], s[0:1], s[26:27]
	s_andn2_b64 vcc, exec, s[0:1]
	s_cbranch_vccnz .LBB0_344
	s_sub_i32 s0, s33, s54
	v_add_u32_e32 v2, s0, v214
	v_cmp_lt_u32_e32 vcc, s66, v2
	v_add_u32_e32 v255, s0, v215
	v_cmp_lt_u32_e64 s[26:27], s66, v255
	v_cndmask_b32_e32 v80, v200, v80, vcc
	v_add_u32_e32 v2, s0, v216
	v_cmp_lt_u32_e32 vcc, s66, v2
	v_cndmask_b32_e64 v81, v200, v81, s[26:27]
	v_add_u32_e32 v255, s0, v217
	v_cmp_lt_u32_e64 s[26:27], s66, v255
	v_cndmask_b32_e32 v82, v200, v82, vcc
	v_add_u32_e32 v2, s0, v218
	v_cmp_lt_u32_e32 vcc, s66, v2
	v_cndmask_b32_e64 v83, v200, v83, s[26:27]
	v_add_u32_e32 v255, s0, v219
	v_cmp_lt_u32_e64 s[26:27], s66, v255
	v_cndmask_b32_e32 v84, v200, v84, vcc
	v_add_u32_e32 v2, s0, v220
	v_cmp_lt_u32_e32 vcc, s66, v2
	v_cndmask_b32_e64 v85, v200, v85, s[26:27]
	v_add_u32_e32 v255, s0, v221
	v_cmp_lt_u32_e64 s[26:27], s66, v255
	v_cndmask_b32_e32 v86, v200, v86, vcc
	v_add_u32_e32 v2, s0, v222
	v_cmp_lt_u32_e32 vcc, s66, v2
	v_cndmask_b32_e64 v87, v200, v87, s[26:27]
	v_add_u32_e32 v255, s0, v223
	v_cmp_lt_u32_e64 s[26:27], s66, v255
	v_cndmask_b32_e32 v88, v200, v88, vcc
	v_add_u32_e32 v2, s0, v224
	v_cmp_lt_u32_e32 vcc, s66, v2
	v_cndmask_b32_e64 v89, v200, v89, s[26:27]
	v_add_u32_e32 v255, s0, v225
	v_cmp_lt_u32_e64 s[26:27], s66, v255
	v_cndmask_b32_e32 v90, v200, v90, vcc
	v_add_u32_e32 v2, s0, v226
	v_cmp_lt_u32_e32 vcc, s66, v2
	v_cndmask_b32_e64 v91, v200, v91, s[26:27]
	v_add_u32_e32 v255, s0, v227
	v_cmp_lt_u32_e64 s[26:27], s66, v255
	v_cndmask_b32_e32 v92, v200, v92, vcc
	v_add_u32_e32 v2, s0, v228
	v_cmp_lt_u32_e32 vcc, s66, v2
	v_cndmask_b32_e64 v93, v200, v93, s[26:27]
	v_add_u32_e32 v255, s0, v229
	v_cmp_lt_u32_e64 s[26:27], s66, v255
	v_cndmask_b32_e32 v94, v200, v94, vcc
	s_nop 0
	v_cndmask_b32_e64 v95, v200, v95, s[26:27]
.LBB0_344:
	s_nop 10
	v_max3_f32 v2, v80, s18, v81
	v_max3_f32 v2, v2, v82, v83
	v_max3_f32 v2, v2, v84, v85
	v_max3_f32 v2, v2, v86, v87
	v_max3_f32 v2, v2, v88, v89
	v_max3_f32 v2, v2, v90, v91
	v_max3_f32 v2, v2, v92, v93
	v_max3_f32 v2, v2, v94, v95
	v_mov_b32_e32 v3, v2
	v_mov_b32_e32 v255, v2
	s_nop 1
	v_permlane32_swap_b32_e32 v3, v255
	s_and_b64 vcc, exec, s[40:41]
	s_waitcnt lgkmcnt(0)
	v_max3_f32 v233, v234, v3, v255
	v_sub_f32_e32 v255, v233, v234
	v_cmp_lt_f32_e64 s[98:99], 4.0, v255
	s_nop 1
	v_cndmask_b32_e64 v233, v234, v233, s[98:99]
	v_sub_f32_e32 v2, v80, v233
	v_exp_f32_e32 v235, v2
	v_sub_f32_e32 v2, v81, v233
	v_exp_f32_e32 v236, v2
	v_sub_f32_e32 v2, v82, v233
	v_exp_f32_e32 v237, v2
	v_sub_f32_e32 v2, v83, v233
	v_exp_f32_e32 v238, v2
	v_sub_f32_e32 v2, v84, v233
	v_exp_f32_e32 v239, v2
	v_sub_f32_e32 v2, v85, v233
	v_exp_f32_e32 v240, v2
	v_sub_f32_e32 v2, v86, v233
	v_exp_f32_e32 v241, v2
	v_sub_f32_e32 v2, v87, v233
	v_exp_f32_e32 v242, v2
	v_sub_f32_e32 v2, v88, v233
	v_exp_f32_e32 v243, v2
	v_sub_f32_e32 v2, v89, v233
	v_exp_f32_e32 v244, v2
	v_sub_f32_e32 v2, v90, v233
	v_exp_f32_e32 v245, v2
	v_sub_f32_e32 v2, v91, v233
	v_exp_f32_e32 v246, v2
	v_sub_f32_e32 v2, v92, v233
	v_exp_f32_e32 v247, v2
	v_sub_f32_e32 v2, v93, v233
	v_exp_f32_e32 v248, v2
	v_sub_f32_e32 v2, v94, v233
	v_exp_f32_e32 v249, v2
	v_sub_f32_e32 v2, v95, v233
	v_mfma_f32_32x32x16_bf16 v[80:95], v[168:171], v[112:115], 0
	v_exp_f32_e32 v250, v2
	v_cvt_pk_bf16_f32 v6, v235, v236
	v_cvt_pk_bf16_f32 v7, v237, v238
	v_cvt_pk_bf16_f32 v8, v239, v240
	v_cvt_pk_bf16_f32 v9, v241, v242
	v_cvt_pk_bf16_f32 v2, v243, v244
	v_cvt_pk_bf16_f32 v3, v245, v246
	v_mfma_f32_32x32x16_bf16 v[80:95], v[164:167], v[116:119], v[80:95]
	v_cvt_pk_bf16_f32 v4, v247, v248
	v_cvt_pk_bf16_f32 v5, v249, v250
	v_mfma_f32_32x32x16_bf16 v[80:95], v[10:13], v[120:123], v[80:95]
	v_mfma_f32_32x32x16_bf16 v[80:95], v[160:163], v[124:127], v[80:95]
	s_cbranch_vccnz .LBB0_347
	s_cmp_lt_i32 s3, s62
	s_cselect_b64 s[0:1], -1, 0
	s_cmp_gt_i32 s3, s55
	s_cselect_b64 s[26:27], -1, 0
	s_or_b64 s[0:1], s[0:1], s[26:27]
	s_andn2_b64 vcc, exec, s[0:1]
	s_cbranch_vccnz .LBB0_347
	s_sub_i32 s0, s33, s63
	v_add_u32_e32 v10, s0, v214
	v_cmp_lt_u32_e32 vcc, s66, v10
	v_add_u32_e32 v255, s0, v215
	v_cmp_lt_u32_e64 s[26:27], s66, v255
	v_cndmask_b32_e32 v80, v200, v80, vcc
	v_add_u32_e32 v10, s0, v216
	v_cmp_lt_u32_e32 vcc, s66, v10
	v_cndmask_b32_e64 v81, v200, v81, s[26:27]
	v_add_u32_e32 v255, s0, v217
	v_cmp_lt_u32_e64 s[26:27], s66, v255
	v_cndmask_b32_e32 v82, v200, v82, vcc
	v_add_u32_e32 v10, s0, v218
	v_cmp_lt_u32_e32 vcc, s66, v10
	v_cndmask_b32_e64 v83, v200, v83, s[26:27]
	v_add_u32_e32 v255, s0, v219
	v_cmp_lt_u32_e64 s[26:27], s66, v255
	v_cndmask_b32_e32 v84, v200, v84, vcc
	v_add_u32_e32 v10, s0, v220
	v_cmp_lt_u32_e32 vcc, s66, v10
	v_cndmask_b32_e64 v85, v200, v85, s[26:27]
	v_add_u32_e32 v255, s0, v221
	v_cmp_lt_u32_e64 s[26:27], s66, v255
	v_cndmask_b32_e32 v86, v200, v86, vcc
	v_add_u32_e32 v10, s0, v222
	v_cmp_lt_u32_e32 vcc, s66, v10
	v_cndmask_b32_e64 v87, v200, v87, s[26:27]
	v_add_u32_e32 v255, s0, v223
	v_cmp_lt_u32_e64 s[26:27], s66, v255
	v_cndmask_b32_e32 v88, v200, v88, vcc
	v_add_u32_e32 v10, s0, v224
	v_cmp_lt_u32_e32 vcc, s66, v10
	v_cndmask_b32_e64 v89, v200, v89, s[26:27]
	v_add_u32_e32 v255, s0, v225
	v_cmp_lt_u32_e64 s[26:27], s66, v255
	v_cndmask_b32_e32 v90, v200, v90, vcc
	v_add_u32_e32 v10, s0, v226
	v_cmp_lt_u32_e32 vcc, s66, v10
	v_cndmask_b32_e64 v91, v200, v91, s[26:27]
	v_add_u32_e32 v255, s0, v227
	v_cmp_lt_u32_e64 s[26:27], s66, v255
	v_cndmask_b32_e32 v92, v200, v92, vcc
	v_add_u32_e32 v10, s0, v228
	v_cmp_lt_u32_e32 vcc, s66, v10
	v_cndmask_b32_e64 v93, v200, v93, s[26:27]
	v_add_u32_e32 v255, s0, v229
	v_cmp_lt_u32_e64 s[26:27], s66, v255
	v_cndmask_b32_e32 v94, v200, v94, vcc
	s_nop 0
	v_cndmask_b32_e64 v95, v200, v95, s[26:27]

.LBB0_359:
	ds_read_b128 v[168:171], v213
	ds_read_b128 v[164:167], v213 offset:32
	ds_read_b128 v[10:13], v213 offset:64
	ds_read_b128 v[160:163], v213 offset:96
	v_cndmask_b32_e64 v2, 0, 1, s[34:35]
	s_add_i32 s33, s3, 0xffffff7f
	s_waitcnt lgkmcnt(3)
	v_mfma_f32_32x32x16_bf16 v[80:95], v[168:171], v[96:99], 0
	v_cmp_ne_u32_e64 s[40:41], 1, v2
	s_andn2_b64 vcc, exec, s[34:35]
	s_waitcnt lgkmcnt(2)
	v_mfma_f32_32x32x16_bf16 v[80:95], v[164:167], v[100:103], v[80:95]
	s_waitcnt lgkmcnt(1)
	v_mfma_f32_32x32x16_bf16 v[80:95], v[10:13], v[104:107], v[80:95]
	s_waitcnt lgkmcnt(0)
	v_mfma_f32_32x32x16_bf16 v[80:95], v[160:163], v[108:111], v[80:95]
	s_cbranch_vccnz .LBB0_362
	s_cmp_lt_i32 s3, s46
	s_cselect_b64 s[0:1], -1, 0
	s_cmp_gt_i32 s3, s75
	s_cselect_b64 s[26:27], -1, 0
	s_or_b64 s[0:1], s[0:1], s[26:27]
	s_andn2_b64 vcc, exec, s[0:1]
	s_cbranch_vccnz .LBB0_362
	s_sub_i32 s0, s33, s54
	v_add_u32_e32 v2, s0, v214
	v_cmp_lt_u32_e32 vcc, s66, v2
	v_add_u32_e32 v255, s0, v215
	v_cmp_lt_u32_e64 s[26:27], s66, v255
	v_cndmask_b32_e32 v80, v200, v80, vcc
	v_add_u32_e32 v2, s0, v216
	v_cmp_lt_u32_e32 vcc, s66, v2
	v_cndmask_b32_e64 v81, v200, v81, s[26:27]
	v_add_u32_e32 v255, s0, v217
	v_cmp_lt_u32_e64 s[26:27], s66, v255
	v_cndmask_b32_e32 v82, v200, v82, vcc
	v_add_u32_e32 v2, s0, v218
	v_cmp_lt_u32_e32 vcc, s66, v2
	v_cndmask_b32_e64 v83, v200, v83, s[26:27]
	v_add_u32_e32 v255, s0, v219
	v_cmp_lt_u32_e64 s[26:27], s66, v255
	v_cndmask_b32_e32 v84, v200, v84, vcc
	v_add_u32_e32 v2, s0, v220
	v_cmp_lt_u32_e32 vcc, s66, v2
	v_cndmask_b32_e64 v85, v200, v85, s[26:27]
	v_add_u32_e32 v255, s0, v221
	v_cmp_lt_u32_e64 s[26:27], s66, v255
	v_cndmask_b32_e32 v86, v200, v86, vcc
	v_add_u32_e32 v2, s0, v222
	v_cmp_lt_u32_e32 vcc, s66, v2
	v_cndmask_b32_e64 v87, v200, v87, s[26:27]
	v_add_u32_e32 v255, s0, v223
	v_cmp_lt_u32_e64 s[26:27], s66, v255
	v_cndmask_b32_e32 v88, v200, v88, vcc
	v_add_u32_e32 v2, s0, v224
	v_cmp_lt_u32_e32 vcc, s66, v2
	v_cndmask_b32_e64 v89, v200, v89, s[26:27]
	v_add_u32_e32 v255, s0, v225
	v_cmp_lt_u32_e64 s[26:27], s66, v255
	v_cndmask_b32_e32 v90, v200, v90, vcc
	v_add_u32_e32 v2, s0, v226
	v_cmp_lt_u32_e32 vcc, s66, v2
	v_cndmask_b32_e64 v91, v200, v91, s[26:27]
	v_add_u32_e32 v255, s0, v227
	v_cmp_lt_u32_e64 s[26:27], s66, v255
	v_cndmask_b32_e32 v92, v200, v92, vcc
	v_add_u32_e32 v2, s0, v228
	v_cmp_lt_u32_e32 vcc, s66, v2
	v_cndmask_b32_e64 v93, v200, v93, s[26:27]
	v_add_u32_e32 v255, s0, v229
	v_cmp_lt_u32_e64 s[26:27], s66, v255
	v_cndmask_b32_e32 v94, v200, v94, vcc
	s_nop 0
	v_cndmask_b32_e64 v95, v200, v95, s[26:27]
.LBB0_362:
	s_nop 10
	v_max3_f32 v2, v80, s18, v81
	v_max3_f32 v2, v2, v82, v83
	v_max3_f32 v2, v2, v84, v85
	v_max3_f32 v2, v2, v86, v87
	v_max3_f32 v2, v2, v88, v89
	v_max3_f32 v2, v2, v90, v91
	v_max3_f32 v2, v2, v92, v93
	v_max3_f32 v2, v2, v94, v95
	v_mov_b32_e32 v3, v2
	v_mov_b32_e32 v255, v2
	s_nop 1
	v_permlane32_swap_b32_e32 v3, v255
	s_and_b64 vcc, exec, s[40:41]
	s_waitcnt lgkmcnt(0)
	v_max3_f32 v234, v233, v3, v255
	v_sub_f32_e32 v255, v234, v233
	v_cmp_lt_f32_e64 s[98:99], 4.0, v255
	s_nop 1
	v_cndmask_b32_e64 v234, v233, v234, s[98:99]
	v_sub_f32_e32 v2, v80, v234
	v_exp_f32_e32 v235, v2
	v_sub_f32_e32 v2, v81, v234
	v_exp_f32_e32 v236, v2
	v_sub_f32_e32 v2, v82, v234
	v_exp_f32_e32 v237, v2
	v_sub_f32_e32 v2, v83, v234
	v_exp_f32_e32 v238, v2
	v_sub_f32_e32 v2, v84, v234
	v_exp_f32_e32 v239, v2
	v_sub_f32_e32 v2, v85, v234
	v_exp_f32_e32 v240, v2
	v_sub_f32_e32 v2, v86, v234
	v_exp_f32_e32 v241, v2
	v_sub_f32_e32 v2, v87, v234
	v_exp_f32_e32 v242, v2
	v_sub_f32_e32 v2, v88, v234
	v_exp_f32_e32 v243, v2
	v_sub_f32_e32 v2, v89, v234
	v_exp_f32_e32 v244, v2
	v_sub_f32_e32 v2, v90, v234
	v_exp_f32_e32 v245, v2
	v_sub_f32_e32 v2, v91, v234
	v_exp_f32_e32 v246, v2
	v_sub_f32_e32 v2, v92, v234
	v_exp_f32_e32 v247, v2
	v_sub_f32_e32 v2, v93, v234
	v_exp_f32_e32 v248, v2
	v_sub_f32_e32 v2, v94, v234
	v_exp_f32_e32 v249, v2
	v_sub_f32_e32 v2, v95, v234
	v_mfma_f32_32x32x16_bf16 v[80:95], v[168:171], v[112:115], 0
	v_exp_f32_e32 v250, v2
	v_cvt_pk_bf16_f32 v6, v235, v236
	v_cvt_pk_bf16_f32 v7, v237, v238
	v_cvt_pk_bf16_f32 v8, v239, v240
	v_cvt_pk_bf16_f32 v9, v241, v242
	v_cvt_pk_bf16_f32 v2, v243, v244
	v_cvt_pk_bf16_f32 v3, v245, v246
	v_mfma_f32_32x32x16_bf16 v[80:95], v[164:167], v[116:119], v[80:95]
	v_cvt_pk_bf16_f32 v4, v247, v248
	v_cvt_pk_bf16_f32 v5, v249, v250
	v_mfma_f32_32x32x16_bf16 v[80:95], v[10:13], v[120:123], v[80:95]
	v_mfma_f32_32x32x16_bf16 v[80:95], v[160:163], v[124:127], v[80:95]
	s_cbranch_vccnz .LBB0_365
	s_cmp_lt_i32 s3, s62
	s_cselect_b64 s[0:1], -1, 0
	s_cmp_gt_i32 s3, s55
	s_cselect_b64 s[26:27], -1, 0
	s_or_b64 s[0:1], s[0:1], s[26:27]
	s_andn2_b64 vcc, exec, s[0:1]
	s_cbranch_vccnz .LBB0_365
	s_sub_i32 s0, s33, s63
	v_add_u32_e32 v10, s0, v214
	v_cmp_lt_u32_e32 vcc, s66, v10
	v_add_u32_e32 v255, s0, v215
	v_cmp_lt_u32_e64 s[26:27], s66, v255
	v_cndmask_b32_e32 v80, v200, v80, vcc
	v_add_u32_e32 v10, s0, v216
	v_cmp_lt_u32_e32 vcc, s66, v10
	v_cndmask_b32_e64 v81, v200, v81, s[26:27]
	v_add_u32_e32 v255, s0, v217
	v_cmp_lt_u32_e64 s[26:27], s66, v255
	v_cndmask_b32_e32 v82, v200, v82, vcc
	v_add_u32_e32 v10, s0, v218
	v_cmp_lt_u32_e32 vcc, s66, v10
	v_cndmask_b32_e64 v83, v200, v83, s[26:27]
	v_add_u32_e32 v255, s0, v219
	v_cmp_lt_u32_e64 s[26:27], s66, v255
	v_cndmask_b32_e32 v84, v200, v84, vcc
	v_add_u32_e32 v10, s0, v220
	v_cmp_lt_u32_e32 vcc, s66, v10
	v_cndmask_b32_e64 v85, v200, v85, s[26:27]
	v_add_u32_e32 v255, s0, v221
	v_cmp_lt_u32_e64 s[26:27], s66, v255
	v_cndmask_b32_e32 v86, v200, v86, vcc
	v_add_u32_e32 v10, s0, v222
	v_cmp_lt_u32_e32 vcc, s66, v10
	v_cndmask_b32_e64 v87, v200, v87, s[26:27]
	v_add_u32_e32 v255, s0, v223
	v_cmp_lt_u32_e64 s[26:27], s66, v255
	v_cndmask_b32_e32 v88, v200, v88, vcc
	v_add_u32_e32 v10, s0, v224
	v_cmp_lt_u32_e32 vcc, s66, v10
	v_cndmask_b32_e64 v89, v200, v89, s[26:27]
	v_add_u32_e32 v255, s0, v225
	v_cmp_lt_u32_e64 s[26:27], s66, v255
	v_cndmask_b32_e32 v90, v200, v90, vcc
	v_add_u32_e32 v10, s0, v226
	v_cmp_lt_u32_e32 vcc, s66, v10
	v_cndmask_b32_e64 v91, v200, v91, s[26:27]
	v_add_u32_e32 v255, s0, v227
	v_cmp_lt_u32_e64 s[26:27], s66, v255
	v_cndmask_b32_e32 v92, v200, v92, vcc
	v_add_u32_e32 v10, s0, v228
	v_cmp_lt_u32_e32 vcc, s66, v10
	v_cndmask_b32_e64 v93, v200, v93, s[26:27]
	v_add_u32_e32 v255, s0, v229
	v_cmp_lt_u32_e64 s[26:27], s66, v255
	v_cndmask_b32_e32 v94, v200, v94, vcc
	s_nop 0
	v_cndmask_b32_e64 v95, v200, v95, s[26:27]

.LBB0_375:
	ds_read_b128 v[168:171], v213 offset:9728
	ds_read_b128 v[164:167], v213 offset:9760
	ds_read_b128 v[10:13], v213 offset:9792
	ds_read_b128 v[160:163], v213 offset:9824
	v_cndmask_b32_e64 v2, 0, 1, s[34:35]
	s_add_i32 s2, s3, 0xffffff7f
	s_waitcnt lgkmcnt(3)
	v_mfma_f32_32x32x16_bf16 v[80:95], v[168:171], v[96:99], 0
	v_cmp_ne_u32_e64 s[38:39], 1, v2
	s_andn2_b64 vcc, exec, s[34:35]
	s_waitcnt lgkmcnt(2)
	v_mfma_f32_32x32x16_bf16 v[80:95], v[164:167], v[100:103], v[80:95]
	s_waitcnt lgkmcnt(1)
	v_mfma_f32_32x32x16_bf16 v[80:95], v[10:13], v[104:107], v[80:95]
	s_waitcnt lgkmcnt(0)
	v_mfma_f32_32x32x16_bf16 v[80:95], v[160:163], v[108:111], v[80:95]
	s_cbranch_vccnz .LBB0_378
	s_cmp_lt_i32 s3, s46
	s_cselect_b64 s[0:1], -1, 0
	s_cmp_gt_i32 s3, s75
	s_cselect_b64 s[26:27], -1, 0
	s_or_b64 s[0:1], s[0:1], s[26:27]
	s_andn2_b64 vcc, exec, s[0:1]
	s_cbranch_vccnz .LBB0_378
	s_sub_i32 s0, s2, s54
	v_add_u32_e32 v2, s0, v214
	v_cmp_lt_u32_e32 vcc, s66, v2
	v_add_u32_e32 v255, s0, v215
	v_cmp_lt_u32_e64 s[26:27], s66, v255
	v_cndmask_b32_e32 v80, v200, v80, vcc
	v_add_u32_e32 v2, s0, v216
	v_cmp_lt_u32_e32 vcc, s66, v2
	v_cndmask_b32_e64 v81, v200, v81, s[26:27]
	v_add_u32_e32 v255, s0, v217
	v_cmp_lt_u32_e64 s[26:27], s66, v255
	v_cndmask_b32_e32 v82, v200, v82, vcc
	v_add_u32_e32 v2, s0, v218
	v_cmp_lt_u32_e32 vcc, s66, v2
	v_cndmask_b32_e64 v83, v200, v83, s[26:27]
	v_add_u32_e32 v255, s0, v219
	v_cmp_lt_u32_e64 s[26:27], s66, v255
	v_cndmask_b32_e32 v84, v200, v84, vcc
	v_add_u32_e32 v2, s0, v220
	v_cmp_lt_u32_e32 vcc, s66, v2
	v_cndmask_b32_e64 v85, v200, v85, s[26:27]
	v_add_u32_e32 v255, s0, v221
	v_cmp_lt_u32_e64 s[26:27], s66, v255
	v_cndmask_b32_e32 v86, v200, v86, vcc
	v_add_u32_e32 v2, s0, v222
	v_cmp_lt_u32_e32 vcc, s66, v2
	v_cndmask_b32_e64 v87, v200, v87, s[26:27]
	v_add_u32_e32 v255, s0, v223
	v_cmp_lt_u32_e64 s[26:27], s66, v255
	v_cndmask_b32_e32 v88, v200, v88, vcc
	v_add_u32_e32 v2, s0, v224
	v_cmp_lt_u32_e32 vcc, s66, v2
	v_cndmask_b32_e64 v89, v200, v89, s[26:27]
	v_add_u32_e32 v255, s0, v225
	v_cmp_lt_u32_e64 s[26:27], s66, v255
	v_cndmask_b32_e32 v90, v200, v90, vcc
	v_add_u32_e32 v2, s0, v226
	v_cmp_lt_u32_e32 vcc, s66, v2
	v_cndmask_b32_e64 v91, v200, v91, s[26:27]
	v_add_u32_e32 v255, s0, v227
	v_cmp_lt_u32_e64 s[26:27], s66, v255
	v_cndmask_b32_e32 v92, v200, v92, vcc
	v_add_u32_e32 v2, s0, v228
	v_cmp_lt_u32_e32 vcc, s66, v2
	v_cndmask_b32_e64 v93, v200, v93, s[26:27]
	v_add_u32_e32 v255, s0, v229
	v_cmp_lt_u32_e64 s[26:27], s66, v255
	v_cndmask_b32_e32 v94, v200, v94, vcc
	s_nop 0
	v_cndmask_b32_e64 v95, v200, v95, s[26:27]
.LBB0_378:
	s_nop 10
	v_max3_f32 v2, v80, s18, v81
	v_max3_f32 v2, v2, v82, v83
	v_max3_f32 v2, v2, v84, v85
	v_max3_f32 v2, v2, v86, v87
	v_max3_f32 v2, v2, v88, v89
	v_max3_f32 v2, v2, v90, v91
	v_max3_f32 v2, v2, v92, v93
	v_max3_f32 v2, v2, v94, v95
	v_mov_b32_e32 v3, v2
	v_mov_b32_e32 v255, v2
	s_nop 1
	v_permlane32_swap_b32_e32 v3, v255
	s_and_b64 vcc, exec, s[38:39]
	s_waitcnt lgkmcnt(0)
	v_max3_f32 v231, v234, v3, v255
	v_sub_f32_e32 v255, v231, v234
	v_cmp_lt_f32_e64 s[98:99], 4.0, v255
	s_nop 1
	v_cndmask_b32_e64 v231, v234, v231, s[98:99]
	v_sub_f32_e32 v2, v80, v231
	v_exp_f32_e32 v15, v2
	v_sub_f32_e32 v2, v81, v231
	v_exp_f32_e32 v233, v2
	v_sub_f32_e32 v2, v82, v231
	v_exp_f32_e32 v235, v2
	v_sub_f32_e32 v2, v83, v231
	v_exp_f32_e32 v236, v2
	v_sub_f32_e32 v2, v84, v231
	v_exp_f32_e32 v237, v2
	v_sub_f32_e32 v2, v85, v231
	v_exp_f32_e32 v238, v2
	v_sub_f32_e32 v2, v86, v231
	v_exp_f32_e32 v239, v2
	v_sub_f32_e32 v2, v87, v231
	v_exp_f32_e32 v240, v2
	v_sub_f32_e32 v2, v88, v231
	v_exp_f32_e32 v241, v2
	v_sub_f32_e32 v2, v89, v231
	v_exp_f32_e32 v242, v2
	v_sub_f32_e32 v2, v90, v231
	v_exp_f32_e32 v243, v2
	v_sub_f32_e32 v2, v91, v231
	v_exp_f32_e32 v244, v2
	v_sub_f32_e32 v2, v92, v231
	v_exp_f32_e32 v245, v2
	v_sub_f32_e32 v2, v93, v231
	v_exp_f32_e32 v246, v2
	v_sub_f32_e32 v2, v94, v231
	v_exp_f32_e32 v247, v2
	v_sub_f32_e32 v2, v95, v231
	v_mfma_f32_32x32x16_bf16 v[80:95], v[168:171], v[112:115], 0
	v_exp_f32_e32 v248, v2
	v_cvt_pk_bf16_f32 v6, v15, v233
	v_cvt_pk_bf16_f32 v7, v235, v236
	v_cvt_pk_bf16_f32 v8, v237, v238
	v_cvt_pk_bf16_f32 v9, v239, v240
	v_cvt_pk_bf16_f32 v2, v241, v242
	v_cvt_pk_bf16_f32 v3, v243, v244
	v_mfma_f32_32x32x16_bf16 v[80:95], v[164:167], v[116:119], v[80:95]
	v_cvt_pk_bf16_f32 v4, v245, v246
	v_cvt_pk_bf16_f32 v5, v247, v248
	v_mfma_f32_32x32x16_bf16 v[80:95], v[10:13], v[120:123], v[80:95]
	v_mfma_f32_32x32x16_bf16 v[80:95], v[160:163], v[124:127], v[80:95]
	s_cbranch_vccnz .LBB0_381
	s_cmp_lt_i32 s3, s62
	s_cselect_b64 s[0:1], -1, 0
	s_cmp_gt_i32 s3, s55
	s_cselect_b64 s[26:27], -1, 0
	s_or_b64 s[0:1], s[0:1], s[26:27]
	s_andn2_b64 vcc, exec, s[0:1]
	s_cbranch_vccnz .LBB0_381
	s_sub_i32 s0, s2, s63
	v_add_u32_e32 v10, s0, v214
	v_cmp_lt_u32_e32 vcc, s66, v10
	v_add_u32_e32 v255, s0, v215
	v_cmp_lt_u32_e64 s[26:27], s66, v255
	v_cndmask_b32_e32 v80, v200, v80, vcc
	v_add_u32_e32 v10, s0, v216
	v_cmp_lt_u32_e32 vcc, s66, v10
	v_cndmask_b32_e64 v81, v200, v81, s[26:27]
	v_add_u32_e32 v255, s0, v217
	v_cmp_lt_u32_e64 s[26:27], s66, v255
	v_cndmask_b32_e32 v82, v200, v82, vcc
	v_add_u32_e32 v10, s0, v218
	v_cmp_lt_u32_e32 vcc, s66, v10
	v_cndmask_b32_e64 v83, v200, v83, s[26:27]
	v_add_u32_e32 v255, s0, v219
	v_cmp_lt_u32_e64 s[26:27], s66, v255
	v_cndmask_b32_e32 v84, v200, v84, vcc
	v_add_u32_e32 v10, s0, v220
	v_cmp_lt_u32_e32 vcc, s66, v10
	v_cndmask_b32_e64 v85, v200, v85, s[26:27]
	v_add_u32_e32 v255, s0, v221
	v_cmp_lt_u32_e64 s[26:27], s66, v255
	v_cndmask_b32_e32 v86, v200, v86, vcc
	v_add_u32_e32 v10, s0, v222
	v_cmp_lt_u32_e32 vcc, s66, v10
	v_cndmask_b32_e64 v87, v200, v87, s[26:27]
	v_add_u32_e32 v255, s0, v223
	v_cmp_lt_u32_e64 s[26:27], s66, v255
	v_cndmask_b32_e32 v88, v200, v88, vcc
	v_add_u32_e32 v10, s0, v224
	v_cmp_lt_u32_e32 vcc, s66, v10
	v_cndmask_b32_e64 v89, v200, v89, s[26:27]
	v_add_u32_e32 v255, s0, v225
	v_cmp_lt_u32_e64 s[26:27], s66, v255
	v_cndmask_b32_e32 v90, v200, v90, vcc
	v_add_u32_e32 v10, s0, v226
	v_cmp_lt_u32_e32 vcc, s66, v10
	v_cndmask_b32_e64 v91, v200, v91, s[26:27]
	v_add_u32_e32 v255, s0, v227
	v_cmp_lt_u32_e64 s[26:27], s66, v255
	v_cndmask_b32_e32 v92, v200, v92, vcc
	v_add_u32_e32 v10, s0, v228
	v_cmp_lt_u32_e32 vcc, s66, v10
	v_cndmask_b32_e64 v93, v200, v93, s[26:27]
	v_add_u32_e32 v255, s0, v229
	v_cmp_lt_u32_e64 s[26:27], s66, v255
	v_cndmask_b32_e32 v94, v200, v94, vcc
	s_nop 0
	v_cndmask_b32_e64 v95, v200, v95, s[26:27]
